# diff fast block: float tile position converted once per step pair (exact f32 subtract for the odd step)
# baseline (speedup 1.0000x reference)
.Ldf_fast:
	s_add_i32 s0, s43, 2
	s_waitcnt vmcnt(4) lgkmcnt(0)
	s_barrier
	s_add_i32 s20, s58, s43
	s_cmp_lt_i32 s20, s89
	v_mfma_f32_32x32x16_bf16 v[2:17], v[158:161], v[182:185], v[2:17]
	v_cvt_f32_i32_e32 v198, v197
	s_cselect_b64 s[26:27], -1, 0
	v_add_f32_e32 v98, 0xc2800000, v198
	v_cndmask_b32_e64 v188, -v193, v193, s[26:27]
	v_add_u32_e32 v199, s15, v240
	ds_read_b64_tr_b16 v[200:201], v199 offset:51200
	ds_read_b64_tr_b16 v[202:203], v199 offset:51712
	v_fma_f32 v114, v188, v98, -v233
	v_exp_f32_e32 v66, v66
	v_exp_f32_e32 v67, v67
	v_fmamk_f32 v98, v188, 0x42000000, v114
	v_add_f32_e32 v115, v188, v114
	v_mfma_f32_32x32x16_bf16 v[2:17], v[154:157], v[178:181], v[2:17]
	ds_read_b64_tr_b16 v[182:183], v199 offset:52224
	ds_read_b64_tr_b16 v[184:185], v199 offset:52736
	v_fmamk_f32 v99, v188, 0x42040000, v114
	v_fma_f32 v116, 2.0, v188, v114
	v_exp_f32_e32 v68, v68
	v_exp_f32_e32 v69, v69
	s_waitcnt lgkmcnt(2)
	v_mfma_f32_32x32x16_bf16 v[2:17], v[150:153], v[200:203], v[2:17]
	ds_read_b64_tr_b16 v[178:179], v199 offset:53248
	ds_read_b64_tr_b16 v[180:181], v199 offset:53760
	v_add_f32_e32 v187, v187, v66
	v_fmamk_f32 v100, v188, 0x42080000, v114
	v_fmamk_f32 v117, v188, 0x40400000, v114
	v_cvt_pk_bf16_f32 v174, v66, v67
	v_add_f32_e32 v187, v67, v187
	v_exp_f32_e32 v70, v70
	s_waitcnt lgkmcnt(2)
	v_mfma_f32_32x32x16_bf16 v[2:17], v[146:149], v[182:185], v[2:17]
	ds_read_b64_tr_b16 v[200:201], v199 offset:54272
	ds_read_b64_tr_b16 v[202:203], v199 offset:54784
	v_fma_f32 v101, v188, s16, v114
	v_fma_f32 v102, v188, s17, v114
	v_fmamk_f32 v118, v188, 0x41000000, v114
	v_exp_f32_e32 v71, v71
	v_add_f32_e32 v187, v187, v68
	s_waitcnt lgkmcnt(2)
	v_mfma_f32_32x32x16_bf16 v[18:33], v[158:161], v[178:181], v[18:33]
	ds_read_b64_tr_b16 v[182:183], v199 offset:55296
	ds_read_b64_tr_b16 v[184:185], v199 offset:55808
	v_fmamk_f32 v119, v188, 0x41100000, v114
	v_fmamk_f32 v103, v188, 0x42240000, v114
	v_cvt_pk_bf16_f32 v175, v68, v69
	v_add_f32_e32 v187, v187, v69
	v_exp_f32_e32 v72, v72
	s_waitcnt lgkmcnt(2)
	v_mfma_f32_32x32x16_bf16 v[18:33], v[154:157], v[200:203], v[18:33]
	ds_read_b64_tr_b16 v[178:179], v199 offset:56320
	ds_read_b64_tr_b16 v[180:181], v199 offset:56832
	v_fmamk_f32 v120, v188, 0x41200000, v114
	v_fmamk_f32 v104, v188, 0x42280000, v114
	v_exp_f32_e32 v73, v73
	v_add_f32_e32 v187, v187, v70
	v_cvt_pk_bf16_f32 v176, v70, v71
	s_waitcnt lgkmcnt(2)
	v_mfma_f32_32x32x16_bf16 v[18:33], v[150:153], v[182:185], v[18:33]
	ds_read_b64_tr_b16 v[200:201], v199 offset:57344
	ds_read_b64_tr_b16 v[202:203], v199 offset:57856
	v_fmamk_f32 v121, v188, 0x41300000, v114
	v_fmamk_f32 v105, v188, 0x422c0000, v114
	v_add_f32_e32 v182, v187, v71
	v_exp_f32_e32 v74, v74
	v_exp_f32_e32 v75, v75
	s_waitcnt lgkmcnt(2)
	v_mfma_f32_32x32x16_bf16 v[18:33], v[146:149], v[178:181], v[18:33]
	ds_read_b64_tr_b16 v[204:205], v199 offset:58368
	ds_read_b64_tr_b16 v[206:207], v199 offset:58880
	v_add_f32_e32 v178, v182, v72
	v_fmamk_f32 v106, v188, 0x42400000, v114
	v_fma_f32 v122, v188, s48, v114
	v_fma_f32 v123, v188, s49, v114
	v_cvt_pk_bf16_f32 v177, v72, v73
	v_add_f32_e32 v187, v73, v178
	s_waitcnt lgkmcnt(2)
	v_mfma_f32_32x32x16_bf16 v[34:49], v[158:161], v[200:203], v[34:49]
	ds_read_b64_tr_b16 v[182:183], v199 offset:59392
	ds_read_b64_tr_b16 v[184:185], v199 offset:59904
	v_fmamk_f32 v107, v188, 0x42440000, v114
	v_fmamk_f32 v124, v188, 0x41900000, v114
	v_exp_f32_e32 v76, v76
	v_exp_f32_e32 v77, v77
	s_waitcnt lgkmcnt(2)
	v_mfma_f32_32x32x16_bf16 v[34:49], v[154:157], v[204:207], v[34:49]
	ds_read_b64_tr_b16 v[178:179], v199 offset:60416
	ds_read_b64_tr_b16 v[180:181], v199 offset:60928
	v_add_f32_e32 v187, v187, v74
	v_fmamk_f32 v108, v188, 0x42480000, v114
	v_fmamk_f32 v125, v188, 0x41980000, v114
	v_cvt_pk_bf16_f32 v170, v74, v75
	v_add_f32_e32 v200, v75, v187
	v_exp_f32_e32 v78, v78
	s_add_u32 s6, s76, s62
	s_addc_u32 s7, s77, s63
	s_add_u32 s26, s6, 0x30000
	s_addc_u32 s27, s7, 0
	s_add_u32 s6, s78, s62
	s_addc_u32 s7, s79, s63
	s_add_u32 s70, s6, 0x30000
	s_addc_u32 s71, s7, 0
	s_add_i32 s6, 0, s59
	s_add_i32 s7, s81, s90
	s_add_u32 s84, s26, 0x8000
	s_addc_u32 s85, s27, 0
	s_add_i32 s15, s6, 0x2000
	s_mov_b32 m0, s6
	s_nop 0
	global_load_lds_dwordx4 v191, s[26:27]
	s_mov_b32 m0, s15
	s_nop 0
	global_load_lds_dwordx4 v191, s[84:85]
	s_mov_b32 m0, s21
	s_add_u32 s26, s70, 0x80
	s_addc_u32 s27, s71, 0
	s_add_i32 s6, s7, 0x2000
	s_mov_b32 m0, s7
	s_nop 0
	global_load_lds_dwordx4 v192, s[70:71]
	s_mov_b32 m0, s6
	s_nop 0
	global_load_lds_dwordx4 v192, s[26:27]
	s_mov_b32 m0, s15
	s_waitcnt lgkmcnt(2)
	v_mfma_f32_32x32x16_bf16 v[34:49], v[150:153], v[182:185], v[34:49]
	ds_read_b64_tr_b16 v[202:203], v199 offset:61440
	ds_read_b64_tr_b16 v[204:205], v199 offset:61952
	v_fma_f32 v109, v188, s56, v114
	v_fma_f32 v110, v188, s57, v114
	v_fmamk_f32 v126, v188, 0x41c00000, v114
	v_exp_f32_e32 v79, v79
	v_add_f32_e32 v187, v200, v76
	s_waitcnt lgkmcnt(2)
	v_mfma_f32_32x32x16_bf16 v[34:49], v[146:149], v[178:181], v[34:49]
	ds_read_b64_tr_b16 v[182:183], v199 offset:62464
	ds_read_b64_tr_b16 v[184:185], v199 offset:62976
	v_fmamk_f32 v127, v188, 0x41c80000, v114
	v_fmamk_f32 v111, v188, 0x42640000, v114
	v_cvt_pk_bf16_f32 v171, v76, v77
	v_add_f32_e32 v187, v187, v77
	v_exp_f32_e32 v80, v80
	s_waitcnt lgkmcnt(2)
	v_mfma_f32_32x32x16_bf16 v[50:65], v[158:161], v[202:205], v[50:65]
	ds_read_b64_tr_b16 v[178:179], v199 offset:63488
	ds_read_b64_tr_b16 v[180:181], v199 offset:64000
	v_fmamk_f32 v128, v188, 0x41d00000, v114
	v_fmamk_f32 v112, v188, 0x42680000, v114
	v_exp_f32_e32 v81, v81
	v_add_f32_e32 v187, v187, v78
	v_cvt_pk_bf16_f32 v172, v78, v79
	s_waitcnt lgkmcnt(2)
	v_mfma_f32_32x32x16_bf16 v[50:65], v[154:157], v[182:185], v[50:65]
	ds_read_b64_tr_b16 v[200:201], v199 offset:64512
	ds_read_b64_tr_b16 v[202:203], v199 offset:65024
	v_fmamk_f32 v129, v188, 0x41d80000, v114
	v_fmamk_f32 v113, v188, 0x426c0000, v114
	v_exp_f32_e32 v82, v82
	v_exp_f32_e32 v83, v83
	v_add_f32_e32 v186, v187, v79
	s_waitcnt lgkmcnt(2)
	v_mfma_f32_32x32x16_bf16 v[50:65], v[150:153], v[178:181], v[50:65]
	ds_read_b128 v[182:185], v190 offset:16384
	v_add_f32_e32 v178, v186, v80
	v_cvt_pk_bf16_f32 v173, v80, v81
	v_add_f32_e32 v186, v81, v178
	v_exp_f32_e32 v84, v84
	v_exp_f32_e32 v85, v85
	s_waitcnt lgkmcnt(1)
	v_mfma_f32_32x32x16_bf16 v[50:65], v[146:149], v[200:203], v[50:65]
	ds_read_b128 v[178:181], v190 offset:24576
	v_add_f32_e32 v186, v186, v82
	v_cvt_pk_bf16_f32 v166, v82, v83
	v_add_f32_e32 v199, v83, v186
	v_exp_f32_e32 v86, v86
	v_exp_f32_e32 v87, v87
	s_waitcnt lgkmcnt(1)
	v_mfma_f32_32x32x16_bf16 v[114:129], v[182:185], v[130:133], v[114:129]
	ds_read_b128 v[186:189], v194 offset:16384
	v_add_f32_e32 v182, v199, v84
	v_cvt_pk_bf16_f32 v167, v84, v85
	v_add_f32_e32 v199, v85, v182
	v_exp_f32_e32 v88, v88
	v_exp_f32_e32 v89, v89
	s_waitcnt lgkmcnt(1)
	v_mfma_f32_32x32x16_bf16 v[98:113], v[178:181], v[130:133], v[98:113]
	ds_read_b128 v[182:185], v194 offset:24576
	v_add_f32_e32 v178, v199, v86
	v_cvt_pk_bf16_f32 v168, v86, v87
	v_add_f32_e32 v199, v87, v178
	v_exp_f32_e32 v90, v90
	v_exp_f32_e32 v91, v91
	s_waitcnt lgkmcnt(1)
	v_mfma_f32_32x32x16_bf16 v[114:129], v[186:189], v[134:137], v[114:129]
	ds_read_b128 v[178:181], v195 offset:16384
	v_add_f32_e32 v186, v199, v88
	v_cvt_pk_bf16_f32 v169, v88, v89
	v_add_f32_e32 v199, v89, v186
	v_exp_f32_e32 v92, v92
	v_exp_f32_e32 v93, v93
	s_waitcnt lgkmcnt(1)
	v_mfma_f32_32x32x16_bf16 v[98:113], v[182:185], v[134:137], v[98:113]
	ds_read_b128 v[186:189], v195 offset:24576
	v_add_f32_e32 v182, v199, v90
	v_cvt_pk_bf16_f32 v162, v90, v91
	v_add_f32_e32 v182, v91, v182
	v_exp_f32_e32 v94, v94
	v_exp_f32_e32 v95, v95
	s_waitcnt lgkmcnt(1)
	v_mfma_f32_32x32x16_bf16 v[114:129], v[178:181], v[138:141], v[114:129]
	ds_read_b128 v[200:203], v196 offset:16384
	v_add_f32_e32 v178, v182, v92
	v_cvt_pk_bf16_f32 v163, v92, v93
	v_add_f32_e32 v178, v93, v178
	v_exp_f32_e32 v96, v96
	v_exp_f32_e32 v97, v97
	s_waitcnt lgkmcnt(1)
	v_mfma_f32_32x32x16_bf16 v[98:113], v[186:189], v[138:141], v[98:113]
	ds_read_b128 v[204:207], v196 offset:24576
	v_add_f32_e32 v165, v178, v94
	v_add_f32_e32 v165, v95, v165
	v_add_f32_e32 v178, v96, v165
	v_cvt_pk_bf16_f32 v164, v94, v95
	v_cvt_pk_bf16_f32 v165, v96, v97
	v_add_f32_e32 v187, v97, v178
	s_waitcnt lgkmcnt(1)
	v_mfma_f32_32x32x16_bf16 v[114:129], v[200:203], v[142:145], v[114:129]
	v_add_u32_e32 v199, s80, v240
	ds_read_b64_tr_b16 v[182:183], v199 offset:49152
	ds_read_b64_tr_b16 v[184:185], v199 offset:49664
	s_waitcnt lgkmcnt(2)
	v_mfma_f32_32x32x16_bf16 v[98:113], v[204:207], v[142:145], v[98:113]
	ds_read_b64_tr_b16 v[178:179], v199 offset:50176
	ds_read_b64_tr_b16 v[180:181], v199 offset:50688
	s_waitcnt vmcnt(4) lgkmcnt(0)
	s_barrier
	s_add_i32 s6, s81, 0x4000
	s_cmp_lg_u32 s81, 0x10000
	s_cselect_b32 s21, s6, 0
	s_add_i32 s20, s20, 1
	s_cmp_lt_i32 s20, s89
	v_mfma_f32_32x32x16_bf16 v[2:17], v[174:177], v[182:185], v[2:17]
	s_cselect_b64 s[6:7], -1, 0
	v_cndmask_b32_e64 v188, -v193, v193, s[6:7]
	ds_read_b64_tr_b16 v[200:201], v199 offset:51200
	ds_read_b64_tr_b16 v[202:203], v199 offset:51712
	v_fma_f32 v66, v188, v198, -v233
	v_exp_f32_e32 v114, v114
	v_exp_f32_e32 v115, v115
	v_fmamk_f32 v82, v188, 0x42000000, v66
	v_add_f32_e32 v67, v188, v66
	v_mfma_f32_32x32x16_bf16 v[2:17], v[170:173], v[178:181], v[2:17]
	ds_read_b64_tr_b16 v[182:183], v199 offset:52224
	ds_read_b64_tr_b16 v[184:185], v199 offset:52736
	v_fmamk_f32 v83, v188, 0x42040000, v66
	v_fma_f32 v68, 2.0, v188, v66
	v_exp_f32_e32 v116, v116
	v_exp_f32_e32 v117, v117
	s_waitcnt lgkmcnt(2)
	v_mfma_f32_32x32x16_bf16 v[2:17], v[166:169], v[200:203], v[2:17]
	ds_read_b64_tr_b16 v[178:179], v199 offset:53248
	ds_read_b64_tr_b16 v[180:181], v199 offset:53760
	v_add_f32_e32 v187, v187, v114
	v_fmamk_f32 v84, v188, 0x42080000, v66
	v_fmamk_f32 v69, v188, 0x40400000, v66
	v_cvt_pk_bf16_f32 v158, v114, v115
	v_add_f32_e32 v187, v115, v187
	v_exp_f32_e32 v118, v118
	s_waitcnt lgkmcnt(2)
	v_mfma_f32_32x32x16_bf16 v[2:17], v[162:165], v[182:185], v[2:17]
	ds_read_b64_tr_b16 v[200:201], v199 offset:54272
	ds_read_b64_tr_b16 v[202:203], v199 offset:54784
	v_fma_f32 v85, v188, s16, v66
	v_fma_f32 v86, v188, s17, v66
	v_fmamk_f32 v70, v188, 0x41000000, v66
	v_exp_f32_e32 v119, v119
	v_add_f32_e32 v187, v187, v116
	s_waitcnt lgkmcnt(2)
	v_mfma_f32_32x32x16_bf16 v[18:33], v[174:177], v[178:181], v[18:33]
	ds_read_b64_tr_b16 v[182:183], v199 offset:55296
	ds_read_b64_tr_b16 v[184:185], v199 offset:55808
	v_fmamk_f32 v71, v188, 0x41100000, v66
	v_fmamk_f32 v87, v188, 0x42240000, v66
	v_cvt_pk_bf16_f32 v159, v116, v117
	v_add_f32_e32 v187, v187, v117
	v_exp_f32_e32 v120, v120
	s_waitcnt lgkmcnt(2)
	v_mfma_f32_32x32x16_bf16 v[18:33], v[170:173], v[200:203], v[18:33]
	ds_read_b64_tr_b16 v[178:179], v199 offset:56320
	ds_read_b64_tr_b16 v[180:181], v199 offset:56832
	v_fmamk_f32 v72, v188, 0x41200000, v66
	v_fmamk_f32 v88, v188, 0x42280000, v66
	v_exp_f32_e32 v121, v121
	v_add_f32_e32 v187, v187, v118
	v_cvt_pk_bf16_f32 v160, v118, v119
	s_waitcnt lgkmcnt(2)
	v_mfma_f32_32x32x16_bf16 v[18:33], v[166:169], v[182:185], v[18:33]
	ds_read_b64_tr_b16 v[200:201], v199 offset:57344
	ds_read_b64_tr_b16 v[202:203], v199 offset:57856
	v_fmamk_f32 v73, v188, 0x41300000, v66
	v_fmamk_f32 v89, v188, 0x422c0000, v66
	v_add_f32_e32 v182, v187, v119
	v_exp_f32_e32 v122, v122
	v_exp_f32_e32 v123, v123
	s_waitcnt lgkmcnt(2)
	v_mfma_f32_32x32x16_bf16 v[18:33], v[162:165], v[178:181], v[18:33]
	ds_read_b64_tr_b16 v[204:205], v199 offset:58368
	ds_read_b64_tr_b16 v[206:207], v199 offset:58880
	v_add_f32_e32 v178, v182, v120
	v_fmamk_f32 v90, v188, 0x42400000, v66
	v_fma_f32 v74, v188, s48, v66
	v_fma_f32 v75, v188, s49, v66
	v_cvt_pk_bf16_f32 v161, v120, v121
	v_add_f32_e32 v187, v121, v178
	s_waitcnt lgkmcnt(2)
	v_mfma_f32_32x32x16_bf16 v[34:49], v[174:177], v[200:203], v[34:49]
	ds_read_b64_tr_b16 v[182:183], v199 offset:59392
	ds_read_b64_tr_b16 v[184:185], v199 offset:59904
	v_fmamk_f32 v91, v188, 0x42440000, v66
	v_fmamk_f32 v76, v188, 0x41900000, v66
	v_exp_f32_e32 v124, v124
	v_exp_f32_e32 v125, v125
	s_waitcnt lgkmcnt(2)
	v_mfma_f32_32x32x16_bf16 v[34:49], v[170:173], v[204:207], v[34:49]
	ds_read_b64_tr_b16 v[178:179], v199 offset:60416
	ds_read_b64_tr_b16 v[180:181], v199 offset:60928
	v_add_f32_e32 v187, v187, v122
	v_fmamk_f32 v92, v188, 0x42480000, v66
	v_fmamk_f32 v77, v188, 0x41980000, v66
	v_cvt_pk_bf16_f32 v154, v122, v123
	v_add_f32_e32 v198, v123, v187
	v_exp_f32_e32 v126, v126
	s_add_u32 s6, s76, s62
	s_addc_u32 s7, s77, s63
	s_add_u32 s6, s6, 0x40000
	s_addc_u32 s7, s7, 0
	s_add_u32 s15, s78, s62
	s_addc_u32 s20, s79, s63
	s_add_u32 s24, s15, 0x40000
	s_addc_u32 s25, s20, 0
	s_add_i32 s15, 0x4000, s59
	s_add_i32 s20, s21, s90
	s_add_u32 s26, s6, 0x8000
	s_addc_u32 s27, s7, 0
	s_add_i32 s68, s15, 0x2000
	s_mov_b32 m0, s15
	s_nop 0
	global_load_lds_dwordx4 v191, s[6:7]
	s_mov_b32 m0, s68
	s_nop 0
	global_load_lds_dwordx4 v191, s[26:27]
	s_mov_b32 m0, s69
	s_add_u32 s6, s24, 0x80
	s_addc_u32 s7, s25, 0
	s_add_i32 s15, s20, 0x2000
	s_mov_b32 m0, s20
	s_nop 0
	global_load_lds_dwordx4 v192, s[24:25]
	s_mov_b32 m0, s15
	s_nop 0
	global_load_lds_dwordx4 v192, s[6:7]
	s_mov_b32 m0, s26
	s_waitcnt lgkmcnt(2)
	v_mfma_f32_32x32x16_bf16 v[34:49], v[166:169], v[182:185], v[34:49]
	ds_read_b64_tr_b16 v[200:201], v199 offset:61440
	ds_read_b64_tr_b16 v[202:203], v199 offset:61952
	s_add_i32 s6, s80, 0x4000
	s_cmp_lg_u32 s80, 0x10000
	v_fma_f32 v93, v188, s56, v66
	v_fma_f32 v94, v188, s57, v66
	s_cselect_b32 s15, s6, 0
	v_fmamk_f32 v78, v188, 0x41c00000, v66
	v_exp_f32_e32 v127, v127
	v_add_f32_e32 v187, v198, v124
	s_waitcnt lgkmcnt(2)
	v_mfma_f32_32x32x16_bf16 v[34:49], v[162:165], v[178:181], v[34:49]
	ds_read_b64_tr_b16 v[182:183], v199 offset:62464
	ds_read_b64_tr_b16 v[184:185], v199 offset:62976
	v_fmamk_f32 v79, v188, 0x41c80000, v66
	v_fmamk_f32 v95, v188, 0x42640000, v66
	v_cvt_pk_bf16_f32 v155, v124, v125
	v_add_f32_e32 v187, v187, v125
	v_exp_f32_e32 v128, v128
	s_waitcnt lgkmcnt(2)
	v_mfma_f32_32x32x16_bf16 v[50:65], v[174:177], v[200:203], v[50:65]
	ds_read_b64_tr_b16 v[178:179], v199 offset:63488
	ds_read_b64_tr_b16 v[180:181], v199 offset:64000
	v_fmamk_f32 v80, v188, 0x41d00000, v66
	v_fmamk_f32 v96, v188, 0x42680000, v66
	v_exp_f32_e32 v129, v129
	v_add_f32_e32 v187, v187, v126
	v_cvt_pk_bf16_f32 v156, v126, v127
	s_waitcnt lgkmcnt(2)
	v_mfma_f32_32x32x16_bf16 v[50:65], v[170:173], v[182:185], v[50:65]
	ds_read_b64_tr_b16 v[200:201], v199 offset:64512
	ds_read_b64_tr_b16 v[202:203], v199 offset:65024
	v_fmamk_f32 v81, v188, 0x41d80000, v66
	v_fmamk_f32 v97, v188, 0x426c0000, v66
	v_exp_f32_e32 v98, v98
	v_exp_f32_e32 v99, v99
	v_add_f32_e32 v186, v187, v127
	s_waitcnt lgkmcnt(2)
	v_mfma_f32_32x32x16_bf16 v[50:65], v[166:169], v[178:181], v[50:65]
	ds_read_b128 v[182:185], v190 offset:32768
	v_add_f32_e32 v178, v186, v128
	v_cvt_pk_bf16_f32 v157, v128, v129
	v_add_f32_e32 v186, v129, v178
	v_exp_f32_e32 v100, v100
	v_exp_f32_e32 v101, v101
	s_waitcnt lgkmcnt(1)
	v_mfma_f32_32x32x16_bf16 v[50:65], v[162:165], v[200:203], v[50:65]
	ds_read_b128 v[178:181], v190 offset:40960
	v_add_f32_e32 v186, v186, v98
	v_cvt_pk_bf16_f32 v150, v98, v99
	v_add_f32_e32 v198, v99, v186
	v_exp_f32_e32 v102, v102
	v_exp_f32_e32 v103, v103
	s_waitcnt lgkmcnt(1)
	v_mfma_f32_32x32x16_bf16 v[66:81], v[182:185], v[130:133], v[66:81]
	ds_read_b128 v[186:189], v194 offset:32768
	v_add_f32_e32 v182, v198, v100
	v_cvt_pk_bf16_f32 v151, v100, v101
	v_add_f32_e32 v198, v101, v182
	v_exp_f32_e32 v104, v104
	v_exp_f32_e32 v105, v105
	s_waitcnt lgkmcnt(1)
	v_mfma_f32_32x32x16_bf16 v[82:97], v[178:181], v[130:133], v[82:97]
	ds_read_b128 v[182:185], v194 offset:40960
	v_add_f32_e32 v178, v198, v102
	v_cvt_pk_bf16_f32 v152, v102, v103
	v_add_f32_e32 v198, v103, v178
	v_exp_f32_e32 v106, v106
	v_exp_f32_e32 v107, v107
	s_waitcnt lgkmcnt(1)
	v_mfma_f32_32x32x16_bf16 v[66:81], v[186:189], v[134:137], v[66:81]
	ds_read_b128 v[178:181], v195 offset:32768
	v_add_f32_e32 v186, v198, v104
	v_cvt_pk_bf16_f32 v153, v104, v105
	v_add_f32_e32 v198, v105, v186
	v_exp_f32_e32 v108, v108
	v_exp_f32_e32 v109, v109
	s_waitcnt lgkmcnt(1)
	v_mfma_f32_32x32x16_bf16 v[82:97], v[182:185], v[134:137], v[82:97]
	ds_read_b128 v[186:189], v195 offset:40960
	v_add_f32_e32 v182, v198, v106
	v_cvt_pk_bf16_f32 v146, v106, v107
	v_add_f32_e32 v182, v107, v182
	v_exp_f32_e32 v110, v110
	v_exp_f32_e32 v111, v111
	s_waitcnt lgkmcnt(1)
	v_mfma_f32_32x32x16_bf16 v[66:81], v[178:181], v[138:141], v[66:81]
	ds_read_b128 v[198:201], v196 offset:32768
	v_add_f32_e32 v178, v182, v108
	v_cvt_pk_bf16_f32 v147, v108, v109
	v_add_f32_e32 v178, v109, v178
	v_exp_f32_e32 v112, v112
	v_exp_f32_e32 v113, v113
	s_waitcnt lgkmcnt(1)
	v_mfma_f32_32x32x16_bf16 v[82:97], v[186:189], v[138:141], v[82:97]
	ds_read_b128 v[202:205], v196 offset:40960
	v_add_f32_e32 v149, v178, v110
	v_add_f32_e32 v149, v111, v149
	v_add_f32_e32 v178, v112, v149
	v_cvt_pk_bf16_f32 v148, v110, v111
	v_cvt_pk_bf16_f32 v149, v112, v113
	v_add_f32_e32 v187, v113, v178
	s_waitcnt lgkmcnt(1)
	v_mfma_f32_32x32x16_bf16 v[66:81], v[198:201], v[142:145], v[66:81]
	v_add_u32_e32 v199, s15, v240
	ds_read_b64_tr_b16 v[182:183], v199 offset:49152
	ds_read_b64_tr_b16 v[184:185], v199 offset:49664
	s_waitcnt lgkmcnt(2)
	v_mfma_f32_32x32x16_bf16 v[82:97], v[202:205], v[142:145], v[82:97]
	ds_read_b64_tr_b16 v[178:179], v199 offset:50176
	ds_read_b64_tr_b16 v[180:181], v199 offset:50688
	s_add_i32 s6, s15, 0x4000
	s_cmp_lg_u32 s15, 0x10000
	s_cselect_b32 s80, s6, 0
	s_add_i32 s6, s21, 0x4000
	s_cmp_lg_u32 s21, 0x10000
	s_cselect_b32 s81, s6, 0
	s_add_u32 s78, s78, 0x20000
	s_addc_u32 s79, s79, 0
	s_add_u32 s76, s76, 0x20000
	s_addc_u32 s77, s77, 0
	v_add_u32_e32 v197, 0x80, v197
	s_mov_b32 s43, s0
	s_add_i32 s0, s43, 2
	s_waitcnt vmcnt(4) lgkmcnt(0)
	s_barrier
	s_add_i32 s20, s58, s43
	s_cmp_lt_i32 s20, s89
	v_mfma_f32_32x32x16_bf16 v[2:17], v[158:161], v[182:185], v[2:17]
	v_cvt_f32_i32_e32 v198, v197
	s_cselect_b64 s[26:27], -1, 0
	v_add_f32_e32 v98, 0xc2800000, v198
	v_cndmask_b32_e64 v188, -v193, v193, s[26:27]
	ds_read_b64_tr_b16 v[200:201], v199 offset:51200
	ds_read_b64_tr_b16 v[202:203], v199 offset:51712
	v_fma_f32 v114, v188, v98, -v233
	v_exp_f32_e32 v66, v66
	v_exp_f32_e32 v67, v67
	v_fmamk_f32 v98, v188, 0x42000000, v114
	v_add_f32_e32 v115, v188, v114
	v_mfma_f32_32x32x16_bf16 v[2:17], v[154:157], v[178:181], v[2:17]
	ds_read_b64_tr_b16 v[182:183], v199 offset:52224
	ds_read_b64_tr_b16 v[184:185], v199 offset:52736
	v_fmamk_f32 v99, v188, 0x42040000, v114
	v_fma_f32 v116, 2.0, v188, v114
	v_exp_f32_e32 v68, v68
	v_exp_f32_e32 v69, v69
	s_waitcnt lgkmcnt(2)
	v_mfma_f32_32x32x16_bf16 v[2:17], v[150:153], v[200:203], v[2:17]
	ds_read_b64_tr_b16 v[178:179], v199 offset:53248
	ds_read_b64_tr_b16 v[180:181], v199 offset:53760
	v_add_f32_e32 v187, v187, v66
	v_fmamk_f32 v100, v188, 0x42080000, v114
	v_fmamk_f32 v117, v188, 0x40400000, v114
	v_cvt_pk_bf16_f32 v174, v66, v67
	v_add_f32_e32 v187, v67, v187
	v_exp_f32_e32 v70, v70
	s_waitcnt lgkmcnt(2)
	v_mfma_f32_32x32x16_bf16 v[2:17], v[146:149], v[182:185], v[2:17]
	ds_read_b64_tr_b16 v[200:201], v199 offset:54272
	ds_read_b64_tr_b16 v[202:203], v199 offset:54784
	v_fma_f32 v101, v188, s16, v114
	v_fma_f32 v102, v188, s17, v114
	v_fmamk_f32 v118, v188, 0x41000000, v114
	v_exp_f32_e32 v71, v71
	v_add_f32_e32 v187, v187, v68
	s_waitcnt lgkmcnt(2)
	v_mfma_f32_32x32x16_bf16 v[18:33], v[158:161], v[178:181], v[18:33]
	ds_read_b64_tr_b16 v[182:183], v199 offset:55296
	ds_read_b64_tr_b16 v[184:185], v199 offset:55808
	v_fmamk_f32 v119, v188, 0x41100000, v114
	v_fmamk_f32 v103, v188, 0x42240000, v114
	v_cvt_pk_bf16_f32 v175, v68, v69
	v_add_f32_e32 v187, v187, v69
	v_exp_f32_e32 v72, v72
	s_waitcnt lgkmcnt(2)
	v_mfma_f32_32x32x16_bf16 v[18:33], v[154:157], v[200:203], v[18:33]
	ds_read_b64_tr_b16 v[178:179], v199 offset:56320
	ds_read_b64_tr_b16 v[180:181], v199 offset:56832
	v_fmamk_f32 v120, v188, 0x41200000, v114
	v_fmamk_f32 v104, v188, 0x42280000, v114
	v_exp_f32_e32 v73, v73
	v_add_f32_e32 v187, v187, v70
	v_cvt_pk_bf16_f32 v176, v70, v71
	s_waitcnt lgkmcnt(2)
	v_mfma_f32_32x32x16_bf16 v[18:33], v[150:153], v[182:185], v[18:33]
	ds_read_b64_tr_b16 v[200:201], v199 offset:57344
	ds_read_b64_tr_b16 v[202:203], v199 offset:57856
	v_fmamk_f32 v121, v188, 0x41300000, v114
	v_fmamk_f32 v105, v188, 0x422c0000, v114
	v_add_f32_e32 v182, v187, v71
	v_exp_f32_e32 v74, v74
	v_exp_f32_e32 v75, v75
	s_waitcnt lgkmcnt(2)
	v_mfma_f32_32x32x16_bf16 v[18:33], v[146:149], v[178:181], v[18:33]
	ds_read_b64_tr_b16 v[204:205], v199 offset:58368
	ds_read_b64_tr_b16 v[206:207], v199 offset:58880
	v_add_f32_e32 v178, v182, v72
	v_fmamk_f32 v106, v188, 0x42400000, v114
	v_fma_f32 v122, v188, s48, v114
	v_fma_f32 v123, v188, s49, v114
	v_cvt_pk_bf16_f32 v177, v72, v73
	v_add_f32_e32 v187, v73, v178
	s_waitcnt lgkmcnt(2)
	v_mfma_f32_32x32x16_bf16 v[34:49], v[158:161], v[200:203], v[34:49]
	ds_read_b64_tr_b16 v[182:183], v199 offset:59392
	ds_read_b64_tr_b16 v[184:185], v199 offset:59904
	v_fmamk_f32 v107, v188, 0x42440000, v114
	v_fmamk_f32 v124, v188, 0x41900000, v114
	v_exp_f32_e32 v76, v76
	v_exp_f32_e32 v77, v77
	s_waitcnt lgkmcnt(2)
	v_mfma_f32_32x32x16_bf16 v[34:49], v[154:157], v[204:207], v[34:49]
	ds_read_b64_tr_b16 v[178:179], v199 offset:60416
	ds_read_b64_tr_b16 v[180:181], v199 offset:60928
	v_add_f32_e32 v187, v187, v74
	v_fmamk_f32 v108, v188, 0x42480000, v114
	v_fmamk_f32 v125, v188, 0x41980000, v114
	v_cvt_pk_bf16_f32 v170, v74, v75
	v_add_f32_e32 v200, v75, v187
	v_exp_f32_e32 v78, v78
	s_add_u32 s6, s76, s62
	s_addc_u32 s7, s77, s63
	s_add_u32 s26, s6, 0x30000
	s_addc_u32 s27, s7, 0
	s_add_u32 s6, s78, s62
	s_addc_u32 s7, s79, s63
	s_add_u32 s70, s6, 0x30000
	s_addc_u32 s71, s7, 0
	s_add_i32 s6, 0x8000, s59
	s_add_i32 s7, s81, s90
	s_add_u32 s84, s26, 0x8000
	s_addc_u32 s85, s27, 0
	s_add_i32 s15, s6, 0x2000
	s_mov_b32 m0, s6
	s_nop 0
	global_load_lds_dwordx4 v191, s[26:27]
	s_mov_b32 m0, s15
	s_nop 0
	global_load_lds_dwordx4 v191, s[84:85]
	s_mov_b32 m0, s21
	s_add_u32 s26, s70, 0x80
	s_addc_u32 s27, s71, 0
	s_add_i32 s6, s7, 0x2000
	s_mov_b32 m0, s7
	s_nop 0
	global_load_lds_dwordx4 v192, s[70:71]
	s_mov_b32 m0, s6
	s_nop 0
	global_load_lds_dwordx4 v192, s[26:27]
	s_mov_b32 m0, s15
	s_waitcnt lgkmcnt(2)
	v_mfma_f32_32x32x16_bf16 v[34:49], v[150:153], v[182:185], v[34:49]
	ds_read_b64_tr_b16 v[202:203], v199 offset:61440
	ds_read_b64_tr_b16 v[204:205], v199 offset:61952
	v_fma_f32 v109, v188, s56, v114
	v_fma_f32 v110, v188, s57, v114
	v_fmamk_f32 v126, v188, 0x41c00000, v114
	v_exp_f32_e32 v79, v79
	v_add_f32_e32 v187, v200, v76
	s_waitcnt lgkmcnt(2)
	v_mfma_f32_32x32x16_bf16 v[34:49], v[146:149], v[178:181], v[34:49]
	ds_read_b64_tr_b16 v[182:183], v199 offset:62464
	ds_read_b64_tr_b16 v[184:185], v199 offset:62976
	v_fmamk_f32 v127, v188, 0x41c80000, v114
	v_fmamk_f32 v111, v188, 0x42640000, v114
	v_cvt_pk_bf16_f32 v171, v76, v77
	v_add_f32_e32 v187, v187, v77
	v_exp_f32_e32 v80, v80
	s_waitcnt lgkmcnt(2)
	v_mfma_f32_32x32x16_bf16 v[50:65], v[158:161], v[202:205], v[50:65]
	ds_read_b64_tr_b16 v[178:179], v199 offset:63488
	ds_read_b64_tr_b16 v[180:181], v199 offset:64000
	v_fmamk_f32 v128, v188, 0x41d00000, v114
	v_fmamk_f32 v112, v188, 0x42680000, v114
	v_exp_f32_e32 v81, v81
	v_add_f32_e32 v187, v187, v78
	v_cvt_pk_bf16_f32 v172, v78, v79
	s_waitcnt lgkmcnt(2)
	v_mfma_f32_32x32x16_bf16 v[50:65], v[154:157], v[182:185], v[50:65]
	ds_read_b64_tr_b16 v[200:201], v199 offset:64512
	ds_read_b64_tr_b16 v[202:203], v199 offset:65024
	v_fmamk_f32 v129, v188, 0x41d80000, v114
	v_fmamk_f32 v113, v188, 0x426c0000, v114
	v_exp_f32_e32 v82, v82
	v_exp_f32_e32 v83, v83
	v_add_f32_e32 v186, v187, v79
	s_waitcnt lgkmcnt(2)
	v_mfma_f32_32x32x16_bf16 v[50:65], v[150:153], v[178:181], v[50:65]
	ds_read_b128 v[182:185], v190
	v_add_f32_e32 v178, v186, v80
	v_cvt_pk_bf16_f32 v173, v80, v81
	v_add_f32_e32 v186, v81, v178
	v_exp_f32_e32 v84, v84
	v_exp_f32_e32 v85, v85
	s_waitcnt lgkmcnt(1)
	v_mfma_f32_32x32x16_bf16 v[50:65], v[146:149], v[200:203], v[50:65]
	ds_read_b128 v[178:181], v190 offset:8192
	v_add_f32_e32 v186, v186, v82
	v_cvt_pk_bf16_f32 v166, v82, v83
	v_add_f32_e32 v199, v83, v186
	v_exp_f32_e32 v86, v86
	v_exp_f32_e32 v87, v87
	s_waitcnt lgkmcnt(1)
	v_mfma_f32_32x32x16_bf16 v[114:129], v[182:185], v[130:133], v[114:129]
	ds_read_b128 v[186:189], v194
	v_add_f32_e32 v182, v199, v84
	v_cvt_pk_bf16_f32 v167, v84, v85
	v_add_f32_e32 v199, v85, v182
	v_exp_f32_e32 v88, v88
	v_exp_f32_e32 v89, v89
	s_waitcnt lgkmcnt(1)
	v_mfma_f32_32x32x16_bf16 v[98:113], v[178:181], v[130:133], v[98:113]
	ds_read_b128 v[182:185], v194 offset:8192
	v_add_f32_e32 v178, v199, v86
	v_cvt_pk_bf16_f32 v168, v86, v87
	v_add_f32_e32 v199, v87, v178
	v_exp_f32_e32 v90, v90
	v_exp_f32_e32 v91, v91
	s_waitcnt lgkmcnt(1)
	v_mfma_f32_32x32x16_bf16 v[114:129], v[186:189], v[134:137], v[114:129]
	ds_read_b128 v[178:181], v195
	v_add_f32_e32 v186, v199, v88
	v_cvt_pk_bf16_f32 v169, v88, v89
	v_add_f32_e32 v199, v89, v186
	v_exp_f32_e32 v92, v92
	v_exp_f32_e32 v93, v93
	s_waitcnt lgkmcnt(1)
	v_mfma_f32_32x32x16_bf16 v[98:113], v[182:185], v[134:137], v[98:113]
	ds_read_b128 v[186:189], v195 offset:8192
	v_add_f32_e32 v182, v199, v90
	v_cvt_pk_bf16_f32 v162, v90, v91
	v_add_f32_e32 v182, v91, v182
	v_exp_f32_e32 v94, v94
	v_exp_f32_e32 v95, v95
	s_waitcnt lgkmcnt(1)
	v_mfma_f32_32x32x16_bf16 v[114:129], v[178:181], v[138:141], v[114:129]
	ds_read_b128 v[200:203], v196
	v_add_f32_e32 v178, v182, v92
	v_cvt_pk_bf16_f32 v163, v92, v93
	v_add_f32_e32 v178, v93, v178
	v_exp_f32_e32 v96, v96
	v_exp_f32_e32 v97, v97
	s_waitcnt lgkmcnt(1)
	v_mfma_f32_32x32x16_bf16 v[98:113], v[186:189], v[138:141], v[98:113]
	ds_read_b128 v[204:207], v196 offset:8192
	v_add_f32_e32 v165, v178, v94
	v_add_f32_e32 v165, v95, v165
	v_add_f32_e32 v178, v96, v165
	v_cvt_pk_bf16_f32 v164, v94, v95
	v_cvt_pk_bf16_f32 v165, v96, v97
	v_add_f32_e32 v187, v97, v178
	s_waitcnt lgkmcnt(1)
	v_mfma_f32_32x32x16_bf16 v[114:129], v[200:203], v[142:145], v[114:129]
	v_add_u32_e32 v199, s80, v240
	ds_read_b64_tr_b16 v[182:183], v199 offset:49152
	ds_read_b64_tr_b16 v[184:185], v199 offset:49664
	s_waitcnt lgkmcnt(2)
	v_mfma_f32_32x32x16_bf16 v[98:113], v[204:207], v[142:145], v[98:113]
	ds_read_b64_tr_b16 v[178:179], v199 offset:50176
	ds_read_b64_tr_b16 v[180:181], v199 offset:50688
	s_waitcnt vmcnt(4) lgkmcnt(0)
	s_barrier
	s_add_i32 s6, s81, 0x4000
	s_cmp_lg_u32 s81, 0x10000
	s_cselect_b32 s21, s6, 0
	s_add_i32 s20, s20, 1
	s_cmp_lt_i32 s20, s89
	v_mfma_f32_32x32x16_bf16 v[2:17], v[174:177], v[182:185], v[2:17]
	s_cselect_b64 s[6:7], -1, 0
	v_cndmask_b32_e64 v188, -v193, v193, s[6:7]
	ds_read_b64_tr_b16 v[200:201], v199 offset:51200
	ds_read_b64_tr_b16 v[202:203], v199 offset:51712
	v_fma_f32 v66, v188, v198, -v233
	v_exp_f32_e32 v114, v114
	v_exp_f32_e32 v115, v115
	v_fmamk_f32 v82, v188, 0x42000000, v66
	v_add_f32_e32 v67, v188, v66
	v_mfma_f32_32x32x16_bf16 v[2:17], v[170:173], v[178:181], v[2:17]
	ds_read_b64_tr_b16 v[182:183], v199 offset:52224
	ds_read_b64_tr_b16 v[184:185], v199 offset:52736
	v_fmamk_f32 v83, v188, 0x42040000, v66
	v_fma_f32 v68, 2.0, v188, v66
	v_exp_f32_e32 v116, v116
	v_exp_f32_e32 v117, v117
	s_waitcnt lgkmcnt(2)
	v_mfma_f32_32x32x16_bf16 v[2:17], v[166:169], v[200:203], v[2:17]
	ds_read_b64_tr_b16 v[178:179], v199 offset:53248
	ds_read_b64_tr_b16 v[180:181], v199 offset:53760
	v_add_f32_e32 v187, v187, v114
	v_fmamk_f32 v84, v188, 0x42080000, v66
	v_fmamk_f32 v69, v188, 0x40400000, v66
	v_cvt_pk_bf16_f32 v158, v114, v115
	v_add_f32_e32 v187, v115, v187
	v_exp_f32_e32 v118, v118
	s_waitcnt lgkmcnt(2)
	v_mfma_f32_32x32x16_bf16 v[2:17], v[162:165], v[182:185], v[2:17]
	ds_read_b64_tr_b16 v[200:201], v199 offset:54272
	ds_read_b64_tr_b16 v[202:203], v199 offset:54784
	v_fma_f32 v85, v188, s16, v66
	v_fma_f32 v86, v188, s17, v66
	v_fmamk_f32 v70, v188, 0x41000000, v66
	v_exp_f32_e32 v119, v119
	v_add_f32_e32 v187, v187, v116
	s_waitcnt lgkmcnt(2)
	v_mfma_f32_32x32x16_bf16 v[18:33], v[174:177], v[178:181], v[18:33]
	ds_read_b64_tr_b16 v[182:183], v199 offset:55296
	ds_read_b64_tr_b16 v[184:185], v199 offset:55808
	v_fmamk_f32 v71, v188, 0x41100000, v66
	v_fmamk_f32 v87, v188, 0x42240000, v66
	v_cvt_pk_bf16_f32 v159, v116, v117
	v_add_f32_e32 v187, v187, v117
	v_exp_f32_e32 v120, v120
	s_waitcnt lgkmcnt(2)
	v_mfma_f32_32x32x16_bf16 v[18:33], v[170:173], v[200:203], v[18:33]
	ds_read_b64_tr_b16 v[178:179], v199 offset:56320
	ds_read_b64_tr_b16 v[180:181], v199 offset:56832
	v_fmamk_f32 v72, v188, 0x41200000, v66
	v_fmamk_f32 v88, v188, 0x42280000, v66
	v_exp_f32_e32 v121, v121
	v_add_f32_e32 v187, v187, v118
	v_cvt_pk_bf16_f32 v160, v118, v119
	s_waitcnt lgkmcnt(2)
	v_mfma_f32_32x32x16_bf16 v[18:33], v[166:169], v[182:185], v[18:33]
	ds_read_b64_tr_b16 v[200:201], v199 offset:57344
	ds_read_b64_tr_b16 v[202:203], v199 offset:57856
	v_fmamk_f32 v73, v188, 0x41300000, v66
	v_fmamk_f32 v89, v188, 0x422c0000, v66
	v_add_f32_e32 v182, v187, v119
	v_exp_f32_e32 v122, v122
	v_exp_f32_e32 v123, v123
	s_waitcnt lgkmcnt(2)
	v_mfma_f32_32x32x16_bf16 v[18:33], v[162:165], v[178:181], v[18:33]
	ds_read_b64_tr_b16 v[204:205], v199 offset:58368
	ds_read_b64_tr_b16 v[206:207], v199 offset:58880
	v_add_f32_e32 v178, v182, v120
	v_fmamk_f32 v90, v188, 0x42400000, v66
	v_fma_f32 v74, v188, s48, v66
	v_fma_f32 v75, v188, s49, v66
	v_cvt_pk_bf16_f32 v161, v120, v121
	v_add_f32_e32 v187, v121, v178
	s_waitcnt lgkmcnt(2)
	v_mfma_f32_32x32x16_bf16 v[34:49], v[174:177], v[200:203], v[34:49]
	ds_read_b64_tr_b16 v[182:183], v199 offset:59392
	ds_read_b64_tr_b16 v[184:185], v199 offset:59904
	v_fmamk_f32 v91, v188, 0x42440000, v66
	v_fmamk_f32 v76, v188, 0x41900000, v66
	v_exp_f32_e32 v124, v124
	v_exp_f32_e32 v125, v125
	s_waitcnt lgkmcnt(2)
	v_mfma_f32_32x32x16_bf16 v[34:49], v[170:173], v[204:207], v[34:49]
	ds_read_b64_tr_b16 v[178:179], v199 offset:60416
	ds_read_b64_tr_b16 v[180:181], v199 offset:60928
	v_add_f32_e32 v187, v187, v122
	v_fmamk_f32 v92, v188, 0x42480000, v66
	v_fmamk_f32 v77, v188, 0x41980000, v66
	v_cvt_pk_bf16_f32 v154, v122, v123
	v_add_f32_e32 v198, v123, v187
	v_exp_f32_e32 v126, v126
	s_add_u32 s6, s76, s62
	s_addc_u32 s7, s77, s63
	s_add_u32 s6, s6, 0x40000
	s_addc_u32 s7, s7, 0
	s_add_u32 s15, s78, s62
	s_addc_u32 s20, s79, s63
	s_add_u32 s24, s15, 0x40000
	s_addc_u32 s25, s20, 0
	s_add_i32 s15, 0, s59
	s_add_i32 s20, s21, s90
	s_add_u32 s26, s6, 0x8000
	s_addc_u32 s27, s7, 0
	s_add_i32 s68, s15, 0x2000
	s_mov_b32 m0, s15
	s_nop 0
	global_load_lds_dwordx4 v191, s[6:7]
	s_mov_b32 m0, s68
	s_nop 0
	global_load_lds_dwordx4 v191, s[26:27]
	s_mov_b32 m0, s69
	s_add_u32 s6, s24, 0x80
	s_addc_u32 s7, s25, 0
	s_add_i32 s15, s20, 0x2000
	s_mov_b32 m0, s20
	s_nop 0
	global_load_lds_dwordx4 v192, s[24:25]
	s_mov_b32 m0, s15
	s_nop 0
	global_load_lds_dwordx4 v192, s[6:7]
	s_mov_b32 m0, s26
	s_waitcnt lgkmcnt(2)
	v_mfma_f32_32x32x16_bf16 v[34:49], v[166:169], v[182:185], v[34:49]
	ds_read_b64_tr_b16 v[200:201], v199 offset:61440
	ds_read_b64_tr_b16 v[202:203], v199 offset:61952
	s_add_i32 s6, s80, 0x4000
	s_cmp_lg_u32 s80, 0x10000
	v_fma_f32 v93, v188, s56, v66
	v_fma_f32 v94, v188, s57, v66
	s_cselect_b32 s15, s6, 0
	v_fmamk_f32 v78, v188, 0x41c00000, v66
	v_exp_f32_e32 v127, v127
	v_add_f32_e32 v187, v198, v124
	s_waitcnt lgkmcnt(2)
	v_mfma_f32_32x32x16_bf16 v[34:49], v[162:165], v[178:181], v[34:49]
	ds_read_b64_tr_b16 v[182:183], v199 offset:62464
	ds_read_b64_tr_b16 v[184:185], v199 offset:62976
	v_fmamk_f32 v79, v188, 0x41c80000, v66
	v_fmamk_f32 v95, v188, 0x42640000, v66
	v_cvt_pk_bf16_f32 v155, v124, v125
	v_add_f32_e32 v187, v187, v125
	v_exp_f32_e32 v128, v128
	s_waitcnt lgkmcnt(2)
	v_mfma_f32_32x32x16_bf16 v[50:65], v[174:177], v[200:203], v[50:65]
	ds_read_b64_tr_b16 v[178:179], v199 offset:63488
	ds_read_b64_tr_b16 v[180:181], v199 offset:64000
	v_fmamk_f32 v80, v188, 0x41d00000, v66
	v_fmamk_f32 v96, v188, 0x42680000, v66
	v_exp_f32_e32 v129, v129
	v_add_f32_e32 v187, v187, v126
	v_cvt_pk_bf16_f32 v156, v126, v127
	s_waitcnt lgkmcnt(2)
	v_mfma_f32_32x32x16_bf16 v[50:65], v[170:173], v[182:185], v[50:65]
	ds_read_b64_tr_b16 v[200:201], v199 offset:64512
	ds_read_b64_tr_b16 v[202:203], v199 offset:65024
	v_fmamk_f32 v81, v188, 0x41d80000, v66
	v_fmamk_f32 v97, v188, 0x426c0000, v66
	v_exp_f32_e32 v98, v98
	v_exp_f32_e32 v99, v99
	v_add_f32_e32 v186, v187, v127
	s_waitcnt lgkmcnt(2)
	v_mfma_f32_32x32x16_bf16 v[50:65], v[166:169], v[178:181], v[50:65]
	ds_read_b128 v[182:185], v190 offset:16384
	v_add_f32_e32 v178, v186, v128
	v_cvt_pk_bf16_f32 v157, v128, v129
	v_add_f32_e32 v186, v129, v178
	v_exp_f32_e32 v100, v100
	v_exp_f32_e32 v101, v101
	s_waitcnt lgkmcnt(1)
	v_mfma_f32_32x32x16_bf16 v[50:65], v[162:165], v[200:203], v[50:65]
	ds_read_b128 v[178:181], v190 offset:24576
	v_add_f32_e32 v186, v186, v98
	v_cvt_pk_bf16_f32 v150, v98, v99
	v_add_f32_e32 v198, v99, v186
	v_exp_f32_e32 v102, v102
	v_exp_f32_e32 v103, v103
	s_waitcnt lgkmcnt(1)
	v_mfma_f32_32x32x16_bf16 v[66:81], v[182:185], v[130:133], v[66:81]
	ds_read_b128 v[186:189], v194 offset:16384
	v_add_f32_e32 v182, v198, v100
	v_cvt_pk_bf16_f32 v151, v100, v101
	v_add_f32_e32 v198, v101, v182
	v_exp_f32_e32 v104, v104
	v_exp_f32_e32 v105, v105
	s_waitcnt lgkmcnt(1)
	v_mfma_f32_32x32x16_bf16 v[82:97], v[178:181], v[130:133], v[82:97]
	ds_read_b128 v[182:185], v194 offset:24576
	v_add_f32_e32 v178, v198, v102
	v_cvt_pk_bf16_f32 v152, v102, v103
	v_add_f32_e32 v198, v103, v178
	v_exp_f32_e32 v106, v106
	v_exp_f32_e32 v107, v107
	s_waitcnt lgkmcnt(1)
	v_mfma_f32_32x32x16_bf16 v[66:81], v[186:189], v[134:137], v[66:81]
	ds_read_b128 v[178:181], v195 offset:16384
	v_add_f32_e32 v186, v198, v104
	v_cvt_pk_bf16_f32 v153, v104, v105
	v_add_f32_e32 v198, v105, v186
	v_exp_f32_e32 v108, v108
	v_exp_f32_e32 v109, v109
	s_waitcnt lgkmcnt(1)
	v_mfma_f32_32x32x16_bf16 v[82:97], v[182:185], v[134:137], v[82:97]
	ds_read_b128 v[186:189], v195 offset:24576
	v_add_f32_e32 v182, v198, v106
	v_cvt_pk_bf16_f32 v146, v106, v107
	v_add_f32_e32 v182, v107, v182
	v_exp_f32_e32 v110, v110
	v_exp_f32_e32 v111, v111
	s_waitcnt lgkmcnt(1)
	v_mfma_f32_32x32x16_bf16 v[66:81], v[178:181], v[138:141], v[66:81]
	ds_read_b128 v[198:201], v196 offset:16384
	v_add_f32_e32 v178, v182, v108
	v_cvt_pk_bf16_f32 v147, v108, v109
	v_add_f32_e32 v178, v109, v178
	v_exp_f32_e32 v112, v112
	v_exp_f32_e32 v113, v113
	s_waitcnt lgkmcnt(1)
	v_mfma_f32_32x32x16_bf16 v[82:97], v[186:189], v[138:141], v[82:97]
	ds_read_b128 v[202:205], v196 offset:24576
	v_add_f32_e32 v149, v178, v110
	v_add_f32_e32 v149, v111, v149
	v_add_f32_e32 v178, v112, v149
	v_cvt_pk_bf16_f32 v148, v110, v111
	v_cvt_pk_bf16_f32 v149, v112, v113
	v_add_f32_e32 v187, v113, v178
	s_waitcnt lgkmcnt(1)
	v_mfma_f32_32x32x16_bf16 v[66:81], v[198:201], v[142:145], v[66:81]
	v_add_u32_e32 v199, s15, v240
	ds_read_b64_tr_b16 v[182:183], v199 offset:49152
	ds_read_b64_tr_b16 v[184:185], v199 offset:49664
	s_waitcnt lgkmcnt(2)
	v_mfma_f32_32x32x16_bf16 v[82:97], v[202:205], v[142:145], v[82:97]
	ds_read_b64_tr_b16 v[178:179], v199 offset:50176
	ds_read_b64_tr_b16 v[180:181], v199 offset:50688
	s_add_i32 s6, s15, 0x4000
	s_cmp_lg_u32 s15, 0x10000
	s_cselect_b32 s80, s6, 0
	s_add_i32 s6, s21, 0x4000
	s_cmp_lg_u32 s21, 0x10000
	s_cselect_b32 s81, s6, 0
	s_add_u32 s78, s78, 0x20000
	s_addc_u32 s79, s79, 0
	s_add_u32 s76, s76, 0x20000
	s_addc_u32 s77, s77, 0
	v_add_u32_e32 v197, 0x80, v197
	s_mov_b32 s43, s0
	s_add_i32 s0, s43, 2
	s_waitcnt vmcnt(4) lgkmcnt(0)
	s_barrier
	s_add_i32 s20, s58, s43
	s_cmp_lt_i32 s20, s89
	v_mfma_f32_32x32x16_bf16 v[2:17], v[158:161], v[182:185], v[2:17]
	v_cvt_f32_i32_e32 v198, v197
	s_cselect_b64 s[26:27], -1, 0
	v_add_f32_e32 v98, 0xc2800000, v198
	v_cndmask_b32_e64 v188, -v193, v193, s[26:27]
	ds_read_b64_tr_b16 v[200:201], v199 offset:51200
	ds_read_b64_tr_b16 v[202:203], v199 offset:51712
	v_fma_f32 v114, v188, v98, -v233
	v_exp_f32_e32 v66, v66
	v_exp_f32_e32 v67, v67
	v_fmamk_f32 v98, v188, 0x42000000, v114
	v_add_f32_e32 v115, v188, v114
	v_mfma_f32_32x32x16_bf16 v[2:17], v[154:157], v[178:181], v[2:17]
	ds_read_b64_tr_b16 v[182:183], v199 offset:52224
	ds_read_b64_tr_b16 v[184:185], v199 offset:52736
	v_fmamk_f32 v99, v188, 0x42040000, v114
	v_fma_f32 v116, 2.0, v188, v114
	v_exp_f32_e32 v68, v68
	v_exp_f32_e32 v69, v69
	s_waitcnt lgkmcnt(2)
	v_mfma_f32_32x32x16_bf16 v[2:17], v[150:153], v[200:203], v[2:17]
	ds_read_b64_tr_b16 v[178:179], v199 offset:53248
	ds_read_b64_tr_b16 v[180:181], v199 offset:53760
	v_add_f32_e32 v187, v187, v66
	v_fmamk_f32 v100, v188, 0x42080000, v114
	v_fmamk_f32 v117, v188, 0x40400000, v114
	v_cvt_pk_bf16_f32 v174, v66, v67
	v_add_f32_e32 v187, v67, v187
	v_exp_f32_e32 v70, v70
	s_waitcnt lgkmcnt(2)
	v_mfma_f32_32x32x16_bf16 v[2:17], v[146:149], v[182:185], v[2:17]
	ds_read_b64_tr_b16 v[200:201], v199 offset:54272
	ds_read_b64_tr_b16 v[202:203], v199 offset:54784
	v_fma_f32 v101, v188, s16, v114
	v_fma_f32 v102, v188, s17, v114
	v_fmamk_f32 v118, v188, 0x41000000, v114
	v_exp_f32_e32 v71, v71
	v_add_f32_e32 v187, v187, v68
	s_waitcnt lgkmcnt(2)
	v_mfma_f32_32x32x16_bf16 v[18:33], v[158:161], v[178:181], v[18:33]
	ds_read_b64_tr_b16 v[182:183], v199 offset:55296
	ds_read_b64_tr_b16 v[184:185], v199 offset:55808
	v_fmamk_f32 v119, v188, 0x41100000, v114
	v_fmamk_f32 v103, v188, 0x42240000, v114
	v_cvt_pk_bf16_f32 v175, v68, v69
	v_add_f32_e32 v187, v187, v69
	v_exp_f32_e32 v72, v72
	s_waitcnt lgkmcnt(2)
	v_mfma_f32_32x32x16_bf16 v[18:33], v[154:157], v[200:203], v[18:33]
	ds_read_b64_tr_b16 v[178:179], v199 offset:56320
	ds_read_b64_tr_b16 v[180:181], v199 offset:56832
	v_fmamk_f32 v120, v188, 0x41200000, v114
	v_fmamk_f32 v104, v188, 0x42280000, v114
	v_exp_f32_e32 v73, v73
	v_add_f32_e32 v187, v187, v70
	v_cvt_pk_bf16_f32 v176, v70, v71
	s_waitcnt lgkmcnt(2)
	v_mfma_f32_32x32x16_bf16 v[18:33], v[150:153], v[182:185], v[18:33]
	ds_read_b64_tr_b16 v[200:201], v199 offset:57344
	ds_read_b64_tr_b16 v[202:203], v199 offset:57856
	v_fmamk_f32 v121, v188, 0x41300000, v114
	v_fmamk_f32 v105, v188, 0x422c0000, v114
	v_add_f32_e32 v182, v187, v71
	v_exp_f32_e32 v74, v74
	v_exp_f32_e32 v75, v75
	s_waitcnt lgkmcnt(2)
	v_mfma_f32_32x32x16_bf16 v[18:33], v[146:149], v[178:181], v[18:33]
	ds_read_b64_tr_b16 v[204:205], v199 offset:58368
	ds_read_b64_tr_b16 v[206:207], v199 offset:58880
	v_add_f32_e32 v178, v182, v72
	v_fmamk_f32 v106, v188, 0x42400000, v114
	v_fma_f32 v122, v188, s48, v114
	v_fma_f32 v123, v188, s49, v114
	v_cvt_pk_bf16_f32 v177, v72, v73
	v_add_f32_e32 v187, v73, v178
	s_waitcnt lgkmcnt(2)
	v_mfma_f32_32x32x16_bf16 v[34:49], v[158:161], v[200:203], v[34:49]
	ds_read_b64_tr_b16 v[182:183], v199 offset:59392
	ds_read_b64_tr_b16 v[184:185], v199 offset:59904
	v_fmamk_f32 v107, v188, 0x42440000, v114
	v_fmamk_f32 v124, v188, 0x41900000, v114
	v_exp_f32_e32 v76, v76
	v_exp_f32_e32 v77, v77
	s_waitcnt lgkmcnt(2)
	v_mfma_f32_32x32x16_bf16 v[34:49], v[154:157], v[204:207], v[34:49]
	ds_read_b64_tr_b16 v[178:179], v199 offset:60416
	ds_read_b64_tr_b16 v[180:181], v199 offset:60928
	v_add_f32_e32 v187, v187, v74
	v_fmamk_f32 v108, v188, 0x42480000, v114
	v_fmamk_f32 v125, v188, 0x41980000, v114
	v_cvt_pk_bf16_f32 v170, v74, v75
	v_add_f32_e32 v200, v75, v187
	v_exp_f32_e32 v78, v78
	s_add_u32 s6, s76, s62
	s_addc_u32 s7, s77, s63
	s_add_u32 s26, s6, 0x30000
	s_addc_u32 s27, s7, 0
	s_add_u32 s6, s78, s62
	s_addc_u32 s7, s79, s63
	s_add_u32 s70, s6, 0x30000
	s_addc_u32 s71, s7, 0
	s_add_i32 s6, 0x4000, s59
	s_add_i32 s7, s81, s90
	s_add_u32 s84, s26, 0x8000
	s_addc_u32 s85, s27, 0
	s_add_i32 s15, s6, 0x2000
	s_mov_b32 m0, s6
	s_nop 0
	global_load_lds_dwordx4 v191, s[26:27]
	s_mov_b32 m0, s15
	s_nop 0
	global_load_lds_dwordx4 v191, s[84:85]
	s_mov_b32 m0, s21
	s_add_u32 s26, s70, 0x80
	s_addc_u32 s27, s71, 0
	s_add_i32 s6, s7, 0x2000
	s_mov_b32 m0, s7
	s_nop 0
	global_load_lds_dwordx4 v192, s[70:71]
	s_mov_b32 m0, s6
	s_nop 0
	global_load_lds_dwordx4 v192, s[26:27]
	s_mov_b32 m0, s15
	s_waitcnt lgkmcnt(2)
	v_mfma_f32_32x32x16_bf16 v[34:49], v[150:153], v[182:185], v[34:49]
	ds_read_b64_tr_b16 v[202:203], v199 offset:61440
	ds_read_b64_tr_b16 v[204:205], v199 offset:61952
	v_fma_f32 v109, v188, s56, v114
	v_fma_f32 v110, v188, s57, v114
	v_fmamk_f32 v126, v188, 0x41c00000, v114
	v_exp_f32_e32 v79, v79
	v_add_f32_e32 v187, v200, v76
	s_waitcnt lgkmcnt(2)
	v_mfma_f32_32x32x16_bf16 v[34:49], v[146:149], v[178:181], v[34:49]
	ds_read_b64_tr_b16 v[182:183], v199 offset:62464
	ds_read_b64_tr_b16 v[184:185], v199 offset:62976
	v_fmamk_f32 v127, v188, 0x41c80000, v114
	v_fmamk_f32 v111, v188, 0x42640000, v114
	v_cvt_pk_bf16_f32 v171, v76, v77
	v_add_f32_e32 v187, v187, v77
	v_exp_f32_e32 v80, v80
	s_waitcnt lgkmcnt(2)
	v_mfma_f32_32x32x16_bf16 v[50:65], v[158:161], v[202:205], v[50:65]
	ds_read_b64_tr_b16 v[178:179], v199 offset:63488
	ds_read_b64_tr_b16 v[180:181], v199 offset:64000
	v_fmamk_f32 v128, v188, 0x41d00000, v114
	v_fmamk_f32 v112, v188, 0x42680000, v114
	v_exp_f32_e32 v81, v81
	v_add_f32_e32 v187, v187, v78
	v_cvt_pk_bf16_f32 v172, v78, v79
	s_waitcnt lgkmcnt(2)
	v_mfma_f32_32x32x16_bf16 v[50:65], v[154:157], v[182:185], v[50:65]
	ds_read_b64_tr_b16 v[200:201], v199 offset:64512
	ds_read_b64_tr_b16 v[202:203], v199 offset:65024
	v_fmamk_f32 v129, v188, 0x41d80000, v114
	v_fmamk_f32 v113, v188, 0x426c0000, v114
	v_exp_f32_e32 v82, v82
	v_exp_f32_e32 v83, v83
	v_add_f32_e32 v186, v187, v79
	s_waitcnt lgkmcnt(2)
	v_mfma_f32_32x32x16_bf16 v[50:65], v[150:153], v[178:181], v[50:65]
	ds_read_b128 v[182:185], v190 offset:32768
	v_add_f32_e32 v178, v186, v80
	v_cvt_pk_bf16_f32 v173, v80, v81
	v_add_f32_e32 v186, v81, v178
	v_exp_f32_e32 v84, v84
	v_exp_f32_e32 v85, v85
	s_waitcnt lgkmcnt(1)
	v_mfma_f32_32x32x16_bf16 v[50:65], v[146:149], v[200:203], v[50:65]
	ds_read_b128 v[178:181], v190 offset:40960
	v_add_f32_e32 v186, v186, v82
	v_cvt_pk_bf16_f32 v166, v82, v83
	v_add_f32_e32 v199, v83, v186
	v_exp_f32_e32 v86, v86
	v_exp_f32_e32 v87, v87
	s_waitcnt lgkmcnt(1)
	v_mfma_f32_32x32x16_bf16 v[114:129], v[182:185], v[130:133], v[114:129]
	ds_read_b128 v[186:189], v194 offset:32768
	v_add_f32_e32 v182, v199, v84
	v_cvt_pk_bf16_f32 v167, v84, v85
	v_add_f32_e32 v199, v85, v182
	v_exp_f32_e32 v88, v88
	v_exp_f32_e32 v89, v89
	s_waitcnt lgkmcnt(1)
	v_mfma_f32_32x32x16_bf16 v[98:113], v[178:181], v[130:133], v[98:113]
	ds_read_b128 v[182:185], v194 offset:40960
	v_add_f32_e32 v178, v199, v86
	v_cvt_pk_bf16_f32 v168, v86, v87
	v_add_f32_e32 v199, v87, v178
	v_exp_f32_e32 v90, v90
	v_exp_f32_e32 v91, v91
	s_waitcnt lgkmcnt(1)
	v_mfma_f32_32x32x16_bf16 v[114:129], v[186:189], v[134:137], v[114:129]
	ds_read_b128 v[178:181], v195 offset:32768
	v_add_f32_e32 v186, v199, v88
	v_cvt_pk_bf16_f32 v169, v88, v89
	v_add_f32_e32 v199, v89, v186
	v_exp_f32_e32 v92, v92
	v_exp_f32_e32 v93, v93
	s_waitcnt lgkmcnt(1)
	v_mfma_f32_32x32x16_bf16 v[98:113], v[182:185], v[134:137], v[98:113]
	ds_read_b128 v[186:189], v195 offset:40960
	v_add_f32_e32 v182, v199, v90
	v_cvt_pk_bf16_f32 v162, v90, v91
	v_add_f32_e32 v182, v91, v182
	v_exp_f32_e32 v94, v94
	v_exp_f32_e32 v95, v95
	s_waitcnt lgkmcnt(1)
	v_mfma_f32_32x32x16_bf16 v[114:129], v[178:181], v[138:141], v[114:129]
	ds_read_b128 v[200:203], v196 offset:32768
	v_add_f32_e32 v178, v182, v92
	v_cvt_pk_bf16_f32 v163, v92, v93
	v_add_f32_e32 v178, v93, v178
	v_exp_f32_e32 v96, v96
	v_exp_f32_e32 v97, v97
	s_waitcnt lgkmcnt(1)
	v_mfma_f32_32x32x16_bf16 v[98:113], v[186:189], v[138:141], v[98:113]
	ds_read_b128 v[204:207], v196 offset:40960
	v_add_f32_e32 v165, v178, v94
	v_add_f32_e32 v165, v95, v165
	v_add_f32_e32 v178, v96, v165
	v_cvt_pk_bf16_f32 v164, v94, v95
	v_cvt_pk_bf16_f32 v165, v96, v97
	v_add_f32_e32 v187, v97, v178
	s_waitcnt lgkmcnt(1)
	v_mfma_f32_32x32x16_bf16 v[114:129], v[200:203], v[142:145], v[114:129]
	v_add_u32_e32 v199, s80, v240
	ds_read_b64_tr_b16 v[182:183], v199 offset:49152
	ds_read_b64_tr_b16 v[184:185], v199 offset:49664
	s_waitcnt lgkmcnt(2)
	v_mfma_f32_32x32x16_bf16 v[98:113], v[204:207], v[142:145], v[98:113]
	ds_read_b64_tr_b16 v[178:179], v199 offset:50176
	ds_read_b64_tr_b16 v[180:181], v199 offset:50688
	s_waitcnt vmcnt(4) lgkmcnt(0)
	s_barrier
	s_add_i32 s6, s81, 0x4000
	s_cmp_lg_u32 s81, 0x10000
	s_cselect_b32 s21, s6, 0
	s_add_i32 s20, s20, 1
	s_cmp_lt_i32 s20, s89
	v_mfma_f32_32x32x16_bf16 v[2:17], v[174:177], v[182:185], v[2:17]
	s_cselect_b64 s[6:7], -1, 0
	v_cndmask_b32_e64 v188, -v193, v193, s[6:7]
	ds_read_b64_tr_b16 v[200:201], v199 offset:51200
	ds_read_b64_tr_b16 v[202:203], v199 offset:51712
	v_fma_f32 v66, v188, v198, -v233
	v_exp_f32_e32 v114, v114
	v_exp_f32_e32 v115, v115
	v_fmamk_f32 v82, v188, 0x42000000, v66
	v_add_f32_e32 v67, v188, v66
	v_mfma_f32_32x32x16_bf16 v[2:17], v[170:173], v[178:181], v[2:17]
	ds_read_b64_tr_b16 v[182:183], v199 offset:52224
	ds_read_b64_tr_b16 v[184:185], v199 offset:52736
	v_fmamk_f32 v83, v188, 0x42040000, v66
	v_fma_f32 v68, 2.0, v188, v66
	v_exp_f32_e32 v116, v116
	v_exp_f32_e32 v117, v117
	s_waitcnt lgkmcnt(2)
	v_mfma_f32_32x32x16_bf16 v[2:17], v[166:169], v[200:203], v[2:17]
	ds_read_b64_tr_b16 v[178:179], v199 offset:53248
	ds_read_b64_tr_b16 v[180:181], v199 offset:53760
	v_add_f32_e32 v187, v187, v114
	v_fmamk_f32 v84, v188, 0x42080000, v66
	v_fmamk_f32 v69, v188, 0x40400000, v66
	v_cvt_pk_bf16_f32 v158, v114, v115
	v_add_f32_e32 v187, v115, v187
	v_exp_f32_e32 v118, v118
	s_waitcnt lgkmcnt(2)
	v_mfma_f32_32x32x16_bf16 v[2:17], v[162:165], v[182:185], v[2:17]
	ds_read_b64_tr_b16 v[200:201], v199 offset:54272
	ds_read_b64_tr_b16 v[202:203], v199 offset:54784
	v_fma_f32 v85, v188, s16, v66
	v_fma_f32 v86, v188, s17, v66
	v_fmamk_f32 v70, v188, 0x41000000, v66
	v_exp_f32_e32 v119, v119
	v_add_f32_e32 v187, v187, v116
	s_waitcnt lgkmcnt(2)
	v_mfma_f32_32x32x16_bf16 v[18:33], v[174:177], v[178:181], v[18:33]
	ds_read_b64_tr_b16 v[182:183], v199 offset:55296
	ds_read_b64_tr_b16 v[184:185], v199 offset:55808
	v_fmamk_f32 v71, v188, 0x41100000, v66
	v_fmamk_f32 v87, v188, 0x42240000, v66
	v_cvt_pk_bf16_f32 v159, v116, v117
	v_add_f32_e32 v187, v187, v117
	v_exp_f32_e32 v120, v120
	s_waitcnt lgkmcnt(2)
	v_mfma_f32_32x32x16_bf16 v[18:33], v[170:173], v[200:203], v[18:33]
	ds_read_b64_tr_b16 v[178:179], v199 offset:56320
	ds_read_b64_tr_b16 v[180:181], v199 offset:56832
	v_fmamk_f32 v72, v188, 0x41200000, v66
	v_fmamk_f32 v88, v188, 0x42280000, v66
	v_exp_f32_e32 v121, v121
	v_add_f32_e32 v187, v187, v118
	v_cvt_pk_bf16_f32 v160, v118, v119
	s_waitcnt lgkmcnt(2)
	v_mfma_f32_32x32x16_bf16 v[18:33], v[166:169], v[182:185], v[18:33]
	ds_read_b64_tr_b16 v[200:201], v199 offset:57344
	ds_read_b64_tr_b16 v[202:203], v199 offset:57856
	v_fmamk_f32 v73, v188, 0x41300000, v66
	v_fmamk_f32 v89, v188, 0x422c0000, v66
	v_add_f32_e32 v182, v187, v119
	v_exp_f32_e32 v122, v122
	v_exp_f32_e32 v123, v123
	s_waitcnt lgkmcnt(2)
	v_mfma_f32_32x32x16_bf16 v[18:33], v[162:165], v[178:181], v[18:33]
	ds_read_b64_tr_b16 v[204:205], v199 offset:58368
	ds_read_b64_tr_b16 v[206:207], v199 offset:58880
	v_add_f32_e32 v178, v182, v120
	v_fmamk_f32 v90, v188, 0x42400000, v66
	v_fma_f32 v74, v188, s48, v66
	v_fma_f32 v75, v188, s49, v66
	v_cvt_pk_bf16_f32 v161, v120, v121
	v_add_f32_e32 v187, v121, v178
	s_waitcnt lgkmcnt(2)
	v_mfma_f32_32x32x16_bf16 v[34:49], v[174:177], v[200:203], v[34:49]
	ds_read_b64_tr_b16 v[182:183], v199 offset:59392
	ds_read_b64_tr_b16 v[184:185], v199 offset:59904
	v_fmamk_f32 v91, v188, 0x42440000, v66
	v_fmamk_f32 v76, v188, 0x41900000, v66
	v_exp_f32_e32 v124, v124
	v_exp_f32_e32 v125, v125
	s_waitcnt lgkmcnt(2)
	v_mfma_f32_32x32x16_bf16 v[34:49], v[170:173], v[204:207], v[34:49]
	ds_read_b64_tr_b16 v[178:179], v199 offset:60416
	ds_read_b64_tr_b16 v[180:181], v199 offset:60928
	v_add_f32_e32 v187, v187, v122
	v_fmamk_f32 v92, v188, 0x42480000, v66
	v_fmamk_f32 v77, v188, 0x41980000, v66
	v_cvt_pk_bf16_f32 v154, v122, v123
	v_add_f32_e32 v198, v123, v187
	v_exp_f32_e32 v126, v126
	s_add_u32 s6, s76, s62
	s_addc_u32 s7, s77, s63
	s_add_u32 s6, s6, 0x40000
	s_addc_u32 s7, s7, 0
	s_add_u32 s15, s78, s62
	s_addc_u32 s20, s79, s63
	s_add_u32 s24, s15, 0x40000
	s_addc_u32 s25, s20, 0
	s_add_i32 s15, 0x8000, s59
	s_add_i32 s20, s21, s90
	s_add_u32 s26, s6, 0x8000
	s_addc_u32 s27, s7, 0
	s_add_i32 s68, s15, 0x2000
	s_mov_b32 m0, s15
	s_nop 0
	global_load_lds_dwordx4 v191, s[6:7]
	s_mov_b32 m0, s68
	s_nop 0
	global_load_lds_dwordx4 v191, s[26:27]
	s_mov_b32 m0, s69
	s_add_u32 s6, s24, 0x80
	s_addc_u32 s7, s25, 0
	s_add_i32 s15, s20, 0x2000
	s_mov_b32 m0, s20
	s_nop 0
	global_load_lds_dwordx4 v192, s[24:25]
	s_mov_b32 m0, s15
	s_nop 0
	global_load_lds_dwordx4 v192, s[6:7]
	s_mov_b32 m0, s26
	s_waitcnt lgkmcnt(2)
	v_mfma_f32_32x32x16_bf16 v[34:49], v[166:169], v[182:185], v[34:49]
	ds_read_b64_tr_b16 v[200:201], v199 offset:61440
	ds_read_b64_tr_b16 v[202:203], v199 offset:61952
	s_add_i32 s6, s80, 0x4000
	s_cmp_lg_u32 s80, 0x10000
	v_fma_f32 v93, v188, s56, v66
	v_fma_f32 v94, v188, s57, v66
	s_cselect_b32 s15, s6, 0
	v_fmamk_f32 v78, v188, 0x41c00000, v66
	v_exp_f32_e32 v127, v127
	v_add_f32_e32 v187, v198, v124
	s_waitcnt lgkmcnt(2)
	v_mfma_f32_32x32x16_bf16 v[34:49], v[162:165], v[178:181], v[34:49]
	ds_read_b64_tr_b16 v[182:183], v199 offset:62464
	ds_read_b64_tr_b16 v[184:185], v199 offset:62976
	v_fmamk_f32 v79, v188, 0x41c80000, v66
	v_fmamk_f32 v95, v188, 0x42640000, v66
	v_cvt_pk_bf16_f32 v155, v124, v125
	v_add_f32_e32 v187, v187, v125
	v_exp_f32_e32 v128, v128
	s_waitcnt lgkmcnt(2)
	v_mfma_f32_32x32x16_bf16 v[50:65], v[174:177], v[200:203], v[50:65]
	ds_read_b64_tr_b16 v[178:179], v199 offset:63488
	ds_read_b64_tr_b16 v[180:181], v199 offset:64000
	v_fmamk_f32 v80, v188, 0x41d00000, v66
	v_fmamk_f32 v96, v188, 0x42680000, v66
	v_exp_f32_e32 v129, v129
	v_add_f32_e32 v187, v187, v126
	v_cvt_pk_bf16_f32 v156, v126, v127
	s_waitcnt lgkmcnt(2)
	v_mfma_f32_32x32x16_bf16 v[50:65], v[170:173], v[182:185], v[50:65]
	ds_read_b64_tr_b16 v[200:201], v199 offset:64512
	ds_read_b64_tr_b16 v[202:203], v199 offset:65024
	v_fmamk_f32 v81, v188, 0x41d80000, v66
	v_fmamk_f32 v97, v188, 0x426c0000, v66
	v_exp_f32_e32 v98, v98
	v_exp_f32_e32 v99, v99
	v_add_f32_e32 v186, v187, v127
	s_waitcnt lgkmcnt(2)
	v_mfma_f32_32x32x16_bf16 v[50:65], v[166:169], v[178:181], v[50:65]
	ds_read_b128 v[182:185], v190
	v_add_f32_e32 v178, v186, v128
	v_cvt_pk_bf16_f32 v157, v128, v129
	v_add_f32_e32 v186, v129, v178
	v_exp_f32_e32 v100, v100
	v_exp_f32_e32 v101, v101
	s_waitcnt lgkmcnt(1)
	v_mfma_f32_32x32x16_bf16 v[50:65], v[162:165], v[200:203], v[50:65]
	ds_read_b128 v[178:181], v190 offset:8192
	v_add_f32_e32 v186, v186, v98
	v_cvt_pk_bf16_f32 v150, v98, v99
	v_add_f32_e32 v198, v99, v186
	v_exp_f32_e32 v102, v102
	v_exp_f32_e32 v103, v103
	s_waitcnt lgkmcnt(1)
	v_mfma_f32_32x32x16_bf16 v[66:81], v[182:185], v[130:133], v[66:81]
	ds_read_b128 v[186:189], v194
	v_add_f32_e32 v182, v198, v100
	v_cvt_pk_bf16_f32 v151, v100, v101
	v_add_f32_e32 v198, v101, v182
	v_exp_f32_e32 v104, v104
	v_exp_f32_e32 v105, v105
	s_waitcnt lgkmcnt(1)
	v_mfma_f32_32x32x16_bf16 v[82:97], v[178:181], v[130:133], v[82:97]
	ds_read_b128 v[182:185], v194 offset:8192
	v_add_f32_e32 v178, v198, v102
	v_cvt_pk_bf16_f32 v152, v102, v103
	v_add_f32_e32 v198, v103, v178
	v_exp_f32_e32 v106, v106
	v_exp_f32_e32 v107, v107
	s_waitcnt lgkmcnt(1)
	v_mfma_f32_32x32x16_bf16 v[66:81], v[186:189], v[134:137], v[66:81]
	ds_read_b128 v[178:181], v195
	v_add_f32_e32 v186, v198, v104
	v_cvt_pk_bf16_f32 v153, v104, v105
	v_add_f32_e32 v198, v105, v186
	v_exp_f32_e32 v108, v108
	v_exp_f32_e32 v109, v109
	s_waitcnt lgkmcnt(1)
	v_mfma_f32_32x32x16_bf16 v[82:97], v[182:185], v[134:137], v[82:97]
	ds_read_b128 v[186:189], v195 offset:8192
	v_add_f32_e32 v182, v198, v106
	v_cvt_pk_bf16_f32 v146, v106, v107
	v_add_f32_e32 v182, v107, v182
	v_exp_f32_e32 v110, v110
	v_exp_f32_e32 v111, v111
	s_waitcnt lgkmcnt(1)
	v_mfma_f32_32x32x16_bf16 v[66:81], v[178:181], v[138:141], v[66:81]
	ds_read_b128 v[198:201], v196
	v_add_f32_e32 v178, v182, v108
	v_cvt_pk_bf16_f32 v147, v108, v109
	v_add_f32_e32 v178, v109, v178
	v_exp_f32_e32 v112, v112
	v_exp_f32_e32 v113, v113
	s_waitcnt lgkmcnt(1)
	v_mfma_f32_32x32x16_bf16 v[82:97], v[186:189], v[138:141], v[82:97]
	ds_read_b128 v[202:205], v196 offset:8192
	v_add_f32_e32 v149, v178, v110
	v_add_f32_e32 v149, v111, v149
	v_add_f32_e32 v178, v112, v149
	v_cvt_pk_bf16_f32 v148, v110, v111
	v_cvt_pk_bf16_f32 v149, v112, v113
	v_add_f32_e32 v187, v113, v178
	s_waitcnt lgkmcnt(1)
	v_mfma_f32_32x32x16_bf16 v[66:81], v[198:201], v[142:145], v[66:81]
	v_add_u32_e32 v180, s15, v240
	ds_read_b64_tr_b16 v[182:183], v180 offset:49152
	ds_read_b64_tr_b16 v[184:185], v180 offset:49664
	s_waitcnt lgkmcnt(2)
	v_mfma_f32_32x32x16_bf16 v[82:97], v[202:205], v[142:145], v[82:97]
	ds_read_b64_tr_b16 v[178:179], v180 offset:50176
	ds_read_b64_tr_b16 v[180:181], v180 offset:50688
	s_add_i32 s6, s15, 0x4000
	s_cmp_lg_u32 s15, 0x10000
	s_cselect_b32 s80, s6, 0
	s_add_i32 s6, s21, 0x4000
	s_cmp_lg_u32 s21, 0x10000
	s_cselect_b32 s81, s6, 0
	s_add_u32 s78, s78, 0x20000
	s_addc_u32 s79, s79, 0
	s_add_u32 s76, s76, 0x20000
	s_addc_u32 s77, s77, 0
	v_add_u32_e32 v197, 0x80, v197
	s_mov_b32 s43, s0
	s_branch .LBB0_1377
